# attnprio: static s_setprio 1 for waves 4..7 in the attention fast loop
# speedup vs baseline: 1.0045x; 1.0045x over previous
; __device__ __forceinline__ uint32_t pack2(float a, float b) { uint32_t r; asm("v_cvt_pk_bf16_f32 %0, %1, %2" : "=v"(r) : "v"(a), "v"(b)); return r; }
; #define MFMA16(a, b, c) __builtin_amdgcn_mfma_f32_16x16x32_bf16(a, b, c, 0, 0, 0)
; __device__ __forceinline__ void attn_phase(const Params& p, char* smem) {
;     ...
;       if (active) {
;         const bf16_t* cK = Ks + buf * KT * KLD;
;         const bf16_t* cV = Vt + buf * 64 * VLD;
; #pragma unroll 1
;         for (int ks = 0; ks < 4; ++ks) {
;           uint32_t pfu[4][4];
; #pragma unroll
;           for (int kf = 0; kf < 2; ++kf) {
;             f32x4 sT[4];
; #pragma unroll
;             for (int g = 0; g < 4; ++g) sT[g] = (f32x4){0.f, 0.f, 0.f, 0.f};
; #pragma unroll
;             for (int ds = 0; ds < 3; ++ds) {
;               bf16x8 ka = *(const bf16x8*)(cK + (ks * 32 + kf * 16 + fr) * KLD + ds * 32 + fq * 8);
; #pragma unroll
;               for (int g = 0; g < 4; ++g) sT[g] = MFMA16(ka, qf[g][ds], sT[g]);
;             }
;             if (stab) {
; #pragma unroll
;               for (int g = 0; g < 4; ++g) { sT[g][0] += mneg[g]; sT[g][1] += mneg[g]; sT[g][2] += mneg[g]; sT[g][3] += mneg[g]; }
;             }
; #pragma unroll
;             for (int g = 0; g < 4; ++g) {
;               float p0 = __builtin_amdgcn_exp2f(sT[g][0]), p1 = __builtin_amdgcn_exp2f(sT[g][1]);
;               float p2 = __builtin_amdgcn_exp2f(sT[g][2]), p3 = __builtin_amdgcn_exp2f(sT[g][3]);
;               { float l_ = lrun[g]; l_ += p0; l_ += p1; l_ += p2; l_ += p3; lrun[g] = l_; }
;               pfu[g][kf * 2] = pack2(p0, p1); pfu[g][kf * 2 + 1] = pack2(p2, p3);
;             }
;           }
;           bf16x8 pf[4];
; #pragma unroll
;           for (int g = 0; g < 4; ++g) {
;             union { uint32_t u[4]; bf16x8 v; } cvt;
;             cvt.u[0] = pfu[g][0]; cvt.u[1] = pfu[g][1]; cvt.u[2] = pfu[g][2]; cvt.u[3] = pfu[g][3];
;             pf[g] = cvt.v;
;           }
; #pragma unroll
;           for (int dvf = 0; dvf < 4; ++dvf) {
;             const bf16_t* vp = cV + (dvf * 16 + fr) * VLD + ks * 32 + fq * 4;
;             union { uint2 u[2]; bf16x8 v; } va;
;             va.u[0] = *(const uint2*)(vp);
;             va.u[1] = *(const uint2*)(vp + 16);
; #pragma unroll
;             for (int g = 0; g < 4; ++g) oT[g][dvf] = MFMA16(va.v, pf[g], oT[g][dvf]);
;           }
;         }
.LBB0_413:
	s_and_saveexec_b64 s[10:11], s[40:41]
	s_cbranch_execz .LBB0_420
	v_cndmask_b32_e64 v132, 0, 1, s[6:7]
	s_movk_i32 s17, 0x5000
	v_mul_lo_u32 v133, v132, s17
	s_movk_i32 s17, 0x6800
	v_mul_lo_u32 v132, v132, s17
	v_add_u32_e32 v242, v240, v133
	v_add_u32_e32 v243, v241, v132
	s_mov_b32 s17, 4
	s_and_b64 vcc, exec, s[4:5]
	s_cbranch_vccnz .LBB0_416
	v_readfirstlane_b32 s69, v164
	s_cmpk_lt_u32 s69, 0x100
	s_cbranch_scc1 .Lattn_noprio
	s_setprio 1
.Lattn_noprio:
	v_add_u32_e32 v206, 0xd000, v242
	ds_read_b128 v[132:135], v243
	ds_read_b128 v[136:139], v243 offset:64
	ds_read_b128 v[140:143], v243 offset:128
	s_mov_b32 s17, 3
.Lattn_fast_loop:
	ds_read_b128 v[148:151], v243 offset:3328
	ds_read_b128 v[152:155], v243 offset:3392
	ds_read_b128 v[156:159], v243 offset:3456
	s_waitcnt lgkmcnt(5)
	v_mfma_f32_16x16x32_bf16 v[244:247], v[132:135], v[0:3], 0
	v_mfma_f32_16x16x32_bf16 v[248:251], v[132:135], v[12:15], 0
	v_mfma_f32_16x16x32_bf16 v[208:211], v[132:135], v[24:27], 0
	v_mfma_f32_16x16x32_bf16 v[212:215], v[132:135], v[36:39], 0
	s_waitcnt lgkmcnt(4)
	v_mfma_f32_16x16x32_bf16 v[244:247], v[136:139], v[4:7], v[244:247]
	v_mfma_f32_16x16x32_bf16 v[248:251], v[136:139], v[16:19], v[248:251]
	v_mfma_f32_16x16x32_bf16 v[208:211], v[136:139], v[28:31], v[208:211]
	v_mfma_f32_16x16x32_bf16 v[212:215], v[136:139], v[40:43], v[212:215]
	s_waitcnt lgkmcnt(3)
	v_mfma_f32_16x16x32_bf16 v[244:247], v[140:143], v[8:11], v[244:247]
	v_mfma_f32_16x16x32_bf16 v[248:251], v[140:143], v[20:23], v[248:251]
	v_mfma_f32_16x16x32_bf16 v[208:211], v[140:143], v[32:35], v[208:211]
	v_mfma_f32_16x16x32_bf16 v[212:215], v[140:143], v[44:47], v[212:215]
	s_waitcnt lgkmcnt(2)
	v_mfma_f32_16x16x32_bf16 v[132:135], v[148:151], v[0:3], 0
	v_mfma_f32_16x16x32_bf16 v[136:139], v[148:151], v[12:15], 0
	v_mfma_f32_16x16x32_bf16 v[140:143], v[148:151], v[24:27], 0
	v_mfma_f32_16x16x32_bf16 v[144:147], v[148:151], v[36:39], 0
	s_waitcnt lgkmcnt(1)
	v_exp_f32_e32 v244, v244
	v_exp_f32_e32 v245, v245
	v_exp_f32_e32 v246, v246
	v_exp_f32_e32 v247, v247
	v_exp_f32_e32 v248, v248
	v_mfma_f32_16x16x32_bf16 v[132:135], v[152:155], v[4:7], v[132:135]
	v_exp_f32_e32 v249, v249
	v_exp_f32_e32 v250, v250
	v_exp_f32_e32 v251, v251
	v_add_f32_e32 v195, v195, v244
	v_add_f32_e32 v195, v195, v245
	v_mfma_f32_16x16x32_bf16 v[136:139], v[152:155], v[16:19], v[136:139]
	v_add_f32_e32 v195, v195, v246
	v_add_f32_e32 v195, v195, v247
	v_cvt_pk_bf16_f32 v244, v244, v245
	v_cvt_pk_bf16_f32 v245, v246, v247
	v_add_f32_e32 v194, v194, v248
	v_mfma_f32_16x16x32_bf16 v[140:143], v[152:155], v[28:31], v[140:143]
	v_add_f32_e32 v194, v194, v249
	v_add_f32_e32 v194, v194, v250
	v_add_f32_e32 v194, v194, v251
	v_cvt_pk_bf16_f32 v248, v248, v249
	v_cvt_pk_bf16_f32 v249, v250, v251
	v_mfma_f32_16x16x32_bf16 v[144:147], v[152:155], v[40:43], v[144:147]
	ds_read_b64_tr_b16 v[160:161], v206 offset:96
	ds_read_b64_tr_b16 v[162:163], v206 offset:2656
	ds_read_b64_tr_b16 v[148:149], v206 offset:0
	ds_read_b64_tr_b16 v[150:151], v206 offset:2560
	ds_read_b64_tr_b16 v[152:153], v206 offset:32
	ds_read_b64_tr_b16 v[154:155], v206 offset:2592
	s_waitcnt lgkmcnt(6)
	v_exp_f32_e32 v208, v208
	v_exp_f32_e32 v209, v209
	v_exp_f32_e32 v210, v210
	v_exp_f32_e32 v211, v211
	v_exp_f32_e32 v212, v212
	v_mfma_f32_16x16x32_bf16 v[132:135], v[156:159], v[8:11], v[132:135]
	v_exp_f32_e32 v213, v213
	v_exp_f32_e32 v214, v214
	v_exp_f32_e32 v215, v215
	v_add_f32_e32 v191, v191, v208
	v_add_f32_e32 v191, v191, v209
	v_mfma_f32_16x16x32_bf16 v[136:139], v[156:159], v[20:23], v[136:139]
	v_add_f32_e32 v191, v191, v210
	v_add_f32_e32 v191, v191, v211
	v_cvt_pk_bf16_f32 v208, v208, v209
	v_cvt_pk_bf16_f32 v209, v210, v211
	v_add_f32_e32 v190, v190, v212
	v_mfma_f32_16x16x32_bf16 v[140:143], v[156:159], v[32:35], v[140:143]
	v_add_f32_e32 v190, v190, v213
	v_add_f32_e32 v190, v190, v214
	v_add_f32_e32 v190, v190, v215
	v_cvt_pk_bf16_f32 v212, v212, v213
	v_cvt_pk_bf16_f32 v213, v214, v215
	v_mfma_f32_16x16x32_bf16 v[144:147], v[156:159], v[44:47], v[144:147]
	ds_read_b64_tr_b16 v[156:157], v206 offset:64
	ds_read_b64_tr_b16 v[158:159], v206 offset:2624
	v_add_u32_e32 v243, 0x1a00, v243
	v_exp_f32_e32 v132, v132
	v_exp_f32_e32 v133, v133
	v_exp_f32_e32 v134, v134
	v_exp_f32_e32 v135, v135
	v_add_f32_e32 v195, v195, v132
	v_add_f32_e32 v195, v195, v133
	v_add_f32_e32 v195, v195, v134
	v_add_f32_e32 v195, v195, v135
	v_cvt_pk_bf16_f32 v246, v132, v133
	v_cvt_pk_bf16_f32 v247, v134, v135
	ds_read_b128 v[132:135], v243
	s_waitcnt lgkmcnt(1)
	v_mfma_f32_16x16x32_bf16 v[108:111], v[148:151], v[244:247], v[108:111]
	v_exp_f32_e32 v136, v136
	v_exp_f32_e32 v137, v137
	v_exp_f32_e32 v138, v138
	v_mfma_f32_16x16x32_bf16 v[104:107], v[152:155], v[244:247], v[104:107]
	v_exp_f32_e32 v139, v139
	v_add_f32_e32 v194, v194, v136
	v_add_f32_e32 v194, v194, v137
	v_mfma_f32_16x16x32_bf16 v[100:103], v[156:159], v[244:247], v[100:103]
	v_add_f32_e32 v194, v194, v138
	v_add_f32_e32 v194, v194, v139
	v_cvt_pk_bf16_f32 v250, v136, v137
	v_cvt_pk_bf16_f32 v251, v138, v139
	v_mfma_f32_16x16x32_bf16 v[96:99], v[160:163], v[244:247], v[96:99]
	ds_read_b128 v[136:139], v243 offset:64
	v_mfma_f32_16x16x32_bf16 v[92:95], v[148:151], v[248:251], v[92:95]
	v_exp_f32_e32 v140, v140
	v_exp_f32_e32 v141, v141
	v_exp_f32_e32 v142, v142
	v_mfma_f32_16x16x32_bf16 v[88:91], v[152:155], v[248:251], v[88:91]
	v_exp_f32_e32 v143, v143
	v_add_f32_e32 v191, v191, v140
	v_add_f32_e32 v191, v191, v141
	v_mfma_f32_16x16x32_bf16 v[84:87], v[156:159], v[248:251], v[84:87]
	v_add_f32_e32 v191, v191, v142
	v_add_f32_e32 v191, v191, v143
	v_cvt_pk_bf16_f32 v210, v140, v141
	v_cvt_pk_bf16_f32 v211, v142, v143
	v_mfma_f32_16x16x32_bf16 v[80:83], v[160:163], v[248:251], v[80:83]
	ds_read_b128 v[140:143], v243 offset:128
	v_mfma_f32_16x16x32_bf16 v[76:79], v[148:151], v[208:211], v[76:79]
	v_exp_f32_e32 v144, v144
	v_exp_f32_e32 v145, v145
	v_exp_f32_e32 v146, v146
	v_mfma_f32_16x16x32_bf16 v[72:75], v[152:155], v[208:211], v[72:75]
	v_exp_f32_e32 v147, v147
	v_add_f32_e32 v190, v190, v144
	v_add_f32_e32 v190, v190, v145
	v_mfma_f32_16x16x32_bf16 v[68:71], v[156:159], v[208:211], v[68:71]
	v_add_f32_e32 v190, v190, v146
	v_add_f32_e32 v190, v190, v147
	v_cvt_pk_bf16_f32 v214, v144, v145
	v_cvt_pk_bf16_f32 v215, v146, v147
	v_mfma_f32_16x16x32_bf16 v[64:67], v[160:163], v[208:211], v[64:67]
	v_add_u32_e32 v206, 0x1400, v206
	v_mfma_f32_16x16x32_bf16 v[60:63], v[148:151], v[212:215], v[60:63]
	v_mfma_f32_16x16x32_bf16 v[56:59], v[152:155], v[212:215], v[56:59]
	v_mfma_f32_16x16x32_bf16 v[52:55], v[156:159], v[212:215], v[52:55]
	v_mfma_f32_16x16x32_bf16 v[48:51], v[160:163], v[212:215], v[48:51]
	s_add_i32 s17, s17, -1
	s_cmp_lg_u32 s17, 0
	s_cbranch_scc1 .Lattn_fast_loop
; __device__ __forceinline__ uint32_t pack2(float a, float b) { uint32_t r; asm("v_cvt_pk_bf16_f32 %0, %1, %2" : "=v"(r) : "v"(a), "v"(b)); return r; }
; #define MFMA16(a, b, c) __builtin_amdgcn_mfma_f32_16x16x32_bf16(a, b, c, 0, 0, 0)
; __device__ __forceinline__ void attn_phase(const Params& p, char* smem) {
;     ...
;         for (int ks = 0; ks < 4; ++ks) {
;           uint32_t pfu[4][4];
; #pragma unroll
;           for (int kf = 0; kf < 2; ++kf) {
;             f32x4 sT[4];
; #pragma unroll
;             for (int g = 0; g < 4; ++g) sT[g] = (f32x4){0.f, 0.f, 0.f, 0.f};
; #pragma unroll
;             for (int ds = 0; ds < 3; ++ds) {
;               bf16x8 ka = *(const bf16x8*)(cK + (ks * 32 + kf * 16 + fr) * KLD + ds * 32 + fq * 8);
; #pragma unroll
;               for (int g = 0; g < 4; ++g) sT[g] = MFMA16(ka, qf[g][ds], sT[g]);
;             }
;             if (stab) {
; #pragma unroll
;               for (int g = 0; g < 4; ++g) { sT[g][0] += mneg[g]; sT[g][1] += mneg[g]; sT[g][2] += mneg[g]; sT[g][3] += mneg[g]; }
;             }
; #pragma unroll
;             for (int g = 0; g < 4; ++g) {
;               float p0 = __builtin_amdgcn_exp2f(sT[g][0]), p1 = __builtin_amdgcn_exp2f(sT[g][1]);
;               float p2 = __builtin_amdgcn_exp2f(sT[g][2]), p3 = __builtin_amdgcn_exp2f(sT[g][3]);
;               { float l_ = lrun[g]; l_ += p0; l_ += p1; l_ += p2; l_ += p3; lrun[g] = l_; }
;               pfu[g][kf * 2] = pack2(p0, p1); pfu[g][kf * 2 + 1] = pack2(p2, p3);
;             }
;           }
;           bf16x8 pf[4];
; #pragma unroll
;           for (int g = 0; g < 4; ++g) {
;             union { uint32_t u[4]; bf16x8 v; } cvt;
;             cvt.u[0] = pfu[g][0]; cvt.u[1] = pfu[g][1]; cvt.u[2] = pfu[g][2]; cvt.u[3] = pfu[g][3];
;             pf[g] = cvt.v;
;           }
; #pragma unroll
;           for (int dvf = 0; dvf < 4; ++dvf) {
;             const bf16_t* vp = cV + (dvf * 16 + fr) * VLD + ks * 32 + fq * 4;
;             union { uint2 u[2]; bf16x8 v; } va;
;             va.u[0] = *(const uint2*)(vp);
;             va.u[1] = *(const uint2*)(vp + 16);
; #pragma unroll
;             for (int g = 0; g < 4; ++g) oT[g][dvf] = MFMA16(va.v, pf[g], oT[g][dvf]);
;           }
;         }
	ds_read_b128 v[148:151], v243 offset:3328
	ds_read_b128 v[152:155], v243 offset:3392
	ds_read_b128 v[156:159], v243 offset:3456
	s_waitcnt lgkmcnt(5)
	v_mfma_f32_16x16x32_bf16 v[244:247], v[132:135], v[0:3], 0
	v_mfma_f32_16x16x32_bf16 v[248:251], v[132:135], v[12:15], 0
	v_mfma_f32_16x16x32_bf16 v[208:211], v[132:135], v[24:27], 0
	v_mfma_f32_16x16x32_bf16 v[212:215], v[132:135], v[36:39], 0
	s_waitcnt lgkmcnt(4)
	v_mfma_f32_16x16x32_bf16 v[244:247], v[136:139], v[4:7], v[244:247]
	v_mfma_f32_16x16x32_bf16 v[248:251], v[136:139], v[16:19], v[248:251]
	v_mfma_f32_16x16x32_bf16 v[208:211], v[136:139], v[28:31], v[208:211]
	v_mfma_f32_16x16x32_bf16 v[212:215], v[136:139], v[40:43], v[212:215]
	s_waitcnt lgkmcnt(3)
	v_mfma_f32_16x16x32_bf16 v[244:247], v[140:143], v[8:11], v[244:247]
	v_mfma_f32_16x16x32_bf16 v[248:251], v[140:143], v[20:23], v[248:251]
	v_mfma_f32_16x16x32_bf16 v[208:211], v[140:143], v[32:35], v[208:211]
	v_mfma_f32_16x16x32_bf16 v[212:215], v[140:143], v[44:47], v[212:215]
	s_waitcnt lgkmcnt(2)
	v_mfma_f32_16x16x32_bf16 v[132:135], v[148:151], v[0:3], 0
	v_mfma_f32_16x16x32_bf16 v[136:139], v[148:151], v[12:15], 0
	v_mfma_f32_16x16x32_bf16 v[140:143], v[148:151], v[24:27], 0
	v_mfma_f32_16x16x32_bf16 v[144:147], v[148:151], v[36:39], 0
	s_waitcnt lgkmcnt(1)
	v_exp_f32_e32 v244, v244
	v_exp_f32_e32 v245, v245
	v_exp_f32_e32 v246, v246
	v_exp_f32_e32 v247, v247
	v_exp_f32_e32 v248, v248
	v_mfma_f32_16x16x32_bf16 v[132:135], v[152:155], v[4:7], v[132:135]
	v_exp_f32_e32 v249, v249
	v_exp_f32_e32 v250, v250
	v_exp_f32_e32 v251, v251
	v_add_f32_e32 v195, v195, v244
	v_add_f32_e32 v195, v195, v245
	v_mfma_f32_16x16x32_bf16 v[136:139], v[152:155], v[16:19], v[136:139]
	v_add_f32_e32 v195, v195, v246
	v_add_f32_e32 v195, v195, v247
	v_cvt_pk_bf16_f32 v244, v244, v245
	v_cvt_pk_bf16_f32 v245, v246, v247
	v_add_f32_e32 v194, v194, v248
	v_mfma_f32_16x16x32_bf16 v[140:143], v[152:155], v[28:31], v[140:143]
	v_add_f32_e32 v194, v194, v249
	v_add_f32_e32 v194, v194, v250
	v_add_f32_e32 v194, v194, v251
	v_cvt_pk_bf16_f32 v248, v248, v249
	v_cvt_pk_bf16_f32 v249, v250, v251
	v_mfma_f32_16x16x32_bf16 v[144:147], v[152:155], v[40:43], v[144:147]
	ds_read_b64_tr_b16 v[160:161], v206 offset:96
	ds_read_b64_tr_b16 v[162:163], v206 offset:2656
	ds_read_b64_tr_b16 v[148:149], v206 offset:0
	ds_read_b64_tr_b16 v[150:151], v206 offset:2560
	ds_read_b64_tr_b16 v[152:153], v206 offset:32
	ds_read_b64_tr_b16 v[154:155], v206 offset:2592
	s_waitcnt lgkmcnt(6)
	v_exp_f32_e32 v208, v208
	v_exp_f32_e32 v209, v209
	v_exp_f32_e32 v210, v210
	v_exp_f32_e32 v211, v211
	v_exp_f32_e32 v212, v212
	v_mfma_f32_16x16x32_bf16 v[132:135], v[156:159], v[8:11], v[132:135]
	v_exp_f32_e32 v213, v213
	v_exp_f32_e32 v214, v214
	v_exp_f32_e32 v215, v215
	v_add_f32_e32 v191, v191, v208
	v_add_f32_e32 v191, v191, v209
	v_mfma_f32_16x16x32_bf16 v[136:139], v[156:159], v[20:23], v[136:139]
	v_add_f32_e32 v191, v191, v210
	v_add_f32_e32 v191, v191, v211
	v_cvt_pk_bf16_f32 v208, v208, v209
	v_cvt_pk_bf16_f32 v209, v210, v211
	v_add_f32_e32 v190, v190, v212
	v_mfma_f32_16x16x32_bf16 v[140:143], v[156:159], v[32:35], v[140:143]
	v_add_f32_e32 v190, v190, v213
	v_add_f32_e32 v190, v190, v214
	v_add_f32_e32 v190, v190, v215
	v_cvt_pk_bf16_f32 v212, v212, v213
	v_cvt_pk_bf16_f32 v213, v214, v215
	v_mfma_f32_16x16x32_bf16 v[144:147], v[156:159], v[44:47], v[144:147]
	ds_read_b64_tr_b16 v[156:157], v206 offset:64
	ds_read_b64_tr_b16 v[158:159], v206 offset:2624
	v_exp_f32_e32 v132, v132
	v_exp_f32_e32 v133, v133
	v_exp_f32_e32 v134, v134
	v_exp_f32_e32 v135, v135
	v_add_f32_e32 v195, v195, v132
	v_add_f32_e32 v195, v195, v133
	v_add_f32_e32 v195, v195, v134
	v_add_f32_e32 v195, v195, v135
	v_cvt_pk_bf16_f32 v246, v132, v133
	v_cvt_pk_bf16_f32 v247, v134, v135
	s_waitcnt lgkmcnt(0)
	s_nop 0
	v_mfma_f32_16x16x32_bf16 v[108:111], v[148:151], v[244:247], v[108:111]
	v_exp_f32_e32 v136, v136
	v_exp_f32_e32 v137, v137
	v_exp_f32_e32 v138, v138
	v_mfma_f32_16x16x32_bf16 v[104:107], v[152:155], v[244:247], v[104:107]
	v_exp_f32_e32 v139, v139
	v_add_f32_e32 v194, v194, v136
	v_add_f32_e32 v194, v194, v137
	v_mfma_f32_16x16x32_bf16 v[100:103], v[156:159], v[244:247], v[100:103]
	v_add_f32_e32 v194, v194, v138
	v_add_f32_e32 v194, v194, v139
	v_cvt_pk_bf16_f32 v250, v136, v137
	v_cvt_pk_bf16_f32 v251, v138, v139
	v_mfma_f32_16x16x32_bf16 v[96:99], v[160:163], v[244:247], v[96:99]
	s_nop 0
	v_mfma_f32_16x16x32_bf16 v[92:95], v[148:151], v[248:251], v[92:95]
	v_exp_f32_e32 v140, v140
	v_exp_f32_e32 v141, v141
	v_exp_f32_e32 v142, v142
	v_mfma_f32_16x16x32_bf16 v[88:91], v[152:155], v[248:251], v[88:91]
	v_exp_f32_e32 v143, v143
	v_add_f32_e32 v191, v191, v140
	v_add_f32_e32 v191, v191, v141
	v_mfma_f32_16x16x32_bf16 v[84:87], v[156:159], v[248:251], v[84:87]
	v_add_f32_e32 v191, v191, v142
	v_add_f32_e32 v191, v191, v143
	v_cvt_pk_bf16_f32 v210, v140, v141
	v_cvt_pk_bf16_f32 v211, v142, v143
	v_mfma_f32_16x16x32_bf16 v[80:83], v[160:163], v[248:251], v[80:83]
	s_nop 0
	v_mfma_f32_16x16x32_bf16 v[76:79], v[148:151], v[208:211], v[76:79]
	v_exp_f32_e32 v144, v144
	v_exp_f32_e32 v145, v145
	v_exp_f32_e32 v146, v146
	v_mfma_f32_16x16x32_bf16 v[72:75], v[152:155], v[208:211], v[72:75]
	v_exp_f32_e32 v147, v147
	v_add_f32_e32 v190, v190, v144
	v_add_f32_e32 v190, v190, v145
	v_mfma_f32_16x16x32_bf16 v[68:71], v[156:159], v[208:211], v[68:71]
	v_add_f32_e32 v190, v190, v146
	v_add_f32_e32 v190, v190, v147
	v_cvt_pk_bf16_f32 v214, v144, v145
	v_cvt_pk_bf16_f32 v215, v146, v147
	v_mfma_f32_16x16x32_bf16 v[64:67], v[160:163], v[208:211], v[64:67]
	s_nop 0
	v_mfma_f32_16x16x32_bf16 v[60:63], v[148:151], v[212:215], v[60:63]
	v_mfma_f32_16x16x32_bf16 v[56:59], v[152:155], v[212:215], v[56:59]
	v_mfma_f32_16x16x32_bf16 v[52:55], v[156:159], v[212:215], v[52:55]
	v_mfma_f32_16x16x32_bf16 v[48:51], v[160:163], v[212:215], v[48:51]
	s_setprio 0
	s_branch .LBB0_420
